# attention output epilogue (3 instances): 16 dwordx2 stores per lane merged into 8 dwordx4 via v_permlane32_swap (same bytes, same addresses)
# baseline (speedup 1.0000x reference)
; __device__ __forceinline__ unsigned pk2(float lo, float hi) { f32x2 v = {lo, hi}; bf2_t b = __builtin_convertvector(v, bf2_t); return __builtin_bit_cast(unsigned, b); }
; __device__ __forceinline__ void ssm_gen(LAS unsigned char* lds, const Args& a, int layer, int g, int j8) {
;     ...
;     if (tid < 16) DSK[tid] = a.d_skip[layer * 512 + g * 16 + tid];
; __device__ __forceinline__ void attn_unit(LAS unsigned char* lds, const Args& a, int layer, int b, int nb, int kh, float shift2) {
;     ...
;     la += __shfl_xor(la, 32); lb += __shfl_xor(lb, 32);
;     const float inva = 1.0f / (la + sinkterm), invb = 1.0f / (lb + sinkterm);
;     bf16_t* opa = MIX + tok0 * 1024 + hq * 64 + 4 * hi; bf16_t* opb = opa + 32 * 1024;
; #pragma unroll
;     for (int j = 0; j < 4; ++j) {
;         u32x2 w0, w1, w2, w3;
;         w0.x = pk2(oa0[4 * j] * inva, oa0[4 * j + 1] * inva); w0.y = pk2(oa0[4 * j + 2] * inva, oa0[4 * j + 3] * inva);
;         w1.x = pk2(oa1[4 * j] * inva, oa1[4 * j + 1] * inva); w1.y = pk2(oa1[4 * j + 2] * inva, oa1[4 * j + 3] * inva);
;         w2.x = pk2(ob0[4 * j] * invb, ob0[4 * j + 1] * invb); w2.y = pk2(ob0[4 * j + 2] * invb, ob0[4 * j + 3] * invb);
;         w3.x = pk2(ob1[4 * j] * invb, ob1[4 * j + 1] * invb); w3.y = pk2(ob1[4 * j + 2] * invb, ob1[4 * j + 3] * invb);
;         *(u32x2*)(opa + 8 * j) = w0; *(u32x2*)(opa + 32 + 8 * j) = w1; *(u32x2*)(opb + 8 * j) = w2; *(u32x2*)(opb + 32 + 8 * j) = w3;
;     }
.LBB0_450:
	ds_bpermute_b32 v64, v185, v149
	s_mov_b32 s1, 0x3fb8aa3b
	v_fma_f32 v65, v187, s1, -v186
	v_exp_f32_e32 v65, v65
	ds_bpermute_b32 v66, v185, v148
	s_waitcnt lgkmcnt(1)
	v_add_f32_e32 v64, v149, v64
	v_lshlrev_b32_e32 v200, 1, v188
	v_add_f32_e32 v64, v65, v64
	v_div_scale_f32 v67, s[8:9], v64, v64, 1.0
	v_rcp_f32_e32 v68, v67
	v_div_scale_f32 v69, vcc, 1.0, v64, 1.0
	s_waitcnt lgkmcnt(0)
	v_add_f32_e32 v66, v148, v66
	v_fma_f32 v70, -v67, v68, 1.0
	v_fmac_f32_e32 v68, v70, v68
	v_mul_f32_e32 v70, v69, v68
	v_fma_f32 v71, -v67, v70, v69
	v_add_f32_e32 v65, v65, v66
	v_fmac_f32_e32 v70, v71, v68
	v_div_scale_f32 v66, s[8:9], v65, v65, 1.0
	v_fma_f32 v67, -v67, v70, v69
	v_rcp_f32_e32 v69, v66
	v_div_fmas_f32 v67, v67, v68, v70
	v_div_fixup_f32 v64, v67, v64, 1.0
	v_readlane_b32 s8, v254, 45
	v_fma_f32 v67, -v66, v69, 1.0
	v_fmac_f32_e32 v69, v67, v69
	v_div_scale_f32 v67, vcc, 1.0, v65, 1.0
	v_mul_f32_e32 v68, v67, v69
	v_fma_f32 v70, -v66, v68, v67
	v_fmac_f32_e32 v68, v70, v69
	v_fma_f32 v66, -v66, v68, v67
	v_div_fmas_f32 v66, v66, v69, v68
	v_lshlrev_b64 v[68:69], 11, v[146:147]
	v_readlane_b32 s9, v254, 46
	v_div_fixup_f32 v66, v66, v65, 1.0
	v_lshl_add_u64 v[68:69], s[8:9], 0, v[68:69]
	v_lshl_add_u64 v[68:69], v[144:145], 1, v[68:69]
	v_lshl_add_u64 v[68:69], v[68:69], 0, v[200:201]
	v_and_b32_e32 v72, 32, v243
	v_mov_b32_e32 v73, 0
	v_lshrrev_b32_e32 v72, 2, v72
	s_mov_b32 s1, 0x10000
	v_lshl_add_u64 v[68:69], v[68:69], 0, v[72:73]
	v_pk_mul_f32 v[16:17], v[16:17], v[64:65] op_sel_hi:[1,0]
	v_pk_mul_f32 v[18:19], v[18:19], v[64:65] op_sel_hi:[1,0]
	v_pk_mul_f32 v[20:21], v[20:21], v[64:65] op_sel_hi:[1,0]
	v_pk_mul_f32 v[22:23], v[22:23], v[64:65] op_sel_hi:[1,0]
	v_pk_mul_f32 v[24:25], v[24:25], v[64:65] op_sel_hi:[1,0]
	v_pk_mul_f32 v[26:27], v[26:27], v[64:65] op_sel_hi:[1,0]
	v_pk_mul_f32 v[28:29], v[28:29], v[64:65] op_sel_hi:[1,0]
	v_pk_mul_f32 v[30:31], v[30:31], v[64:65] op_sel_hi:[1,0]
	v_pk_mul_f32 v[48:49], v[48:49], v[64:65] op_sel_hi:[1,0]
	v_pk_mul_f32 v[50:51], v[50:51], v[64:65] op_sel_hi:[1,0]
	v_pk_mul_f32 v[52:53], v[52:53], v[64:65] op_sel_hi:[1,0]
	v_pk_mul_f32 v[54:55], v[54:55], v[64:65] op_sel_hi:[1,0]
	v_pk_mul_f32 v[56:57], v[56:57], v[64:65] op_sel_hi:[1,0]
	v_pk_mul_f32 v[58:59], v[58:59], v[64:65] op_sel_hi:[1,0]
	v_pk_mul_f32 v[60:61], v[60:61], v[64:65] op_sel_hi:[1,0]
	v_pk_mul_f32 v[62:63], v[62:63], v[64:65] op_sel_hi:[1,0]
	v_pk_mul_f32 v[32:33], v[32:33], v[66:67] op_sel_hi:[1,0]
	v_pk_mul_f32 v[34:35], v[34:35], v[66:67] op_sel_hi:[1,0]
	v_pk_mul_f32 v[36:37], v[36:37], v[66:67] op_sel_hi:[1,0]
	v_pk_mul_f32 v[38:39], v[38:39], v[66:67] op_sel_hi:[1,0]
	v_pk_mul_f32 v[40:41], v[40:41], v[66:67] op_sel_hi:[1,0]
	v_pk_mul_f32 v[42:43], v[42:43], v[66:67] op_sel_hi:[1,0]
	v_pk_mul_f32 v[44:45], v[44:45], v[66:67] op_sel_hi:[1,0]
	v_pk_mul_f32 v[46:47], v[46:47], v[66:67] op_sel_hi:[1,0]
	v_pk_mul_f32 v[0:1], v[0:1], v[66:67] op_sel_hi:[1,0]
	v_pk_mul_f32 v[2:3], v[2:3], v[66:67] op_sel_hi:[1,0]
	v_pk_mul_f32 v[4:5], v[4:5], v[66:67] op_sel_hi:[1,0]
	v_pk_mul_f32 v[6:7], v[6:7], v[66:67] op_sel_hi:[1,0]
	v_pk_mul_f32 v[8:9], v[8:9], v[66:67] op_sel_hi:[1,0]
	v_pk_mul_f32 v[10:11], v[10:11], v[66:67] op_sel_hi:[1,0]
	v_pk_mul_f32 v[12:13], v[12:13], v[66:67] op_sel_hi:[1,0]
	v_pk_mul_f32 v[14:15], v[14:15], v[66:67] op_sel_hi:[1,0]
	v_add_co_u32_e32 v70, vcc, s1, v68
	s_nop 1
	v_addc_co_u32_e32 v71, vcc, 0, v69, vcc
	v_cvt_pk_bf16_f32 v16, v16, v17
	v_cvt_pk_bf16_f32 v17, v18, v19
	v_cvt_pk_bf16_f32 v18, v20, v21
	v_cvt_pk_bf16_f32 v19, v22, v23
	v_cvt_pk_bf16_f32 v24, v24, v25
	v_cvt_pk_bf16_f32 v25, v26, v27
	v_cvt_pk_bf16_f32 v26, v28, v29
	v_cvt_pk_bf16_f32 v27, v30, v31
	v_cvt_pk_bf16_f32 v48, v48, v49
	v_cvt_pk_bf16_f32 v49, v50, v51
	v_cvt_pk_bf16_f32 v50, v52, v53
	v_cvt_pk_bf16_f32 v51, v54, v55
	v_cvt_pk_bf16_f32 v56, v56, v57
	v_cvt_pk_bf16_f32 v57, v58, v59
	v_cvt_pk_bf16_f32 v58, v60, v61
	v_cvt_pk_bf16_f32 v59, v62, v63
	v_cvt_pk_bf16_f32 v32, v32, v33
	v_cvt_pk_bf16_f32 v33, v34, v35
	v_cvt_pk_bf16_f32 v34, v36, v37
	v_cvt_pk_bf16_f32 v35, v38, v39
	v_cvt_pk_bf16_f32 v40, v40, v41
	v_cvt_pk_bf16_f32 v41, v42, v43
	v_cvt_pk_bf16_f32 v42, v44, v45
	v_cvt_pk_bf16_f32 v43, v46, v47
	v_cvt_pk_bf16_f32 v0, v0, v1
	v_cvt_pk_bf16_f32 v1, v2, v3
	v_cvt_pk_bf16_f32 v2, v4, v5
	v_cvt_pk_bf16_f32 v3, v6, v7
	v_cvt_pk_bf16_f32 v8, v8, v9
	v_cvt_pk_bf16_f32 v9, v10, v11
	v_cvt_pk_bf16_f32 v10, v12, v13
	v_cvt_pk_bf16_f32 v11, v14, v15
	s_nop 1
	v_permlane32_swap_b32_e32 v16, v18
	v_permlane32_swap_b32_e32 v17, v19
	v_permlane32_swap_b32_e32 v24, v26
	v_permlane32_swap_b32_e32 v25, v27
	v_permlane32_swap_b32_e32 v48, v50
	v_permlane32_swap_b32_e32 v49, v51
	v_permlane32_swap_b32_e32 v56, v58
	v_permlane32_swap_b32_e32 v57, v59
	v_permlane32_swap_b32_e32 v32, v34
	v_permlane32_swap_b32_e32 v33, v35
	v_permlane32_swap_b32_e32 v40, v42
	v_permlane32_swap_b32_e32 v41, v43
	v_permlane32_swap_b32_e32 v0, v2
	v_permlane32_swap_b32_e32 v1, v3
	v_permlane32_swap_b32_e32 v8, v10
	v_permlane32_swap_b32_e32 v9, v11
	global_store_dwordx4 v[68:69], v[16:19], off
	global_store_dwordx4 v[68:69], v[24:27], off offset:32
	global_store_dwordx4 v[68:69], v[48:51], off offset:64
	global_store_dwordx4 v[68:69], v[56:59], off offset:96
	global_store_dwordx4 v[70:71], v[32:35], off
	global_store_dwordx4 v[70:71], v[40:43], off offset:32
	global_store_dwordx4 v[70:71], v[0:3], off offset:64
	global_store_dwordx4 v[70:71], v[8:11], off offset:96
	s_nop 1
	v_readlane_b32 s8, v255, 43
	v_readlane_b32 s9, v255, 44
	s_nop 0
	s_andn2_b64 vcc, exec, s[8:9]
	s_barrier
	s_cbranch_vccnz .LBB0_481
	v_mov_b32_e32 v12, v236
	s_lshr_b32 s10, s49, 3
	s_mov_b32 s11, s59
	v_cmp_gt_i32_e32 vcc, 16, v12
	s_and_saveexec_b64 s[16:17], vcc
	s_cbranch_execz .LBB0_453
	s_lshl_b32 s5, s10, 4
	s_lshl_b32 s7, s52, 9
	s_add_i32 s5, s5, s7
	v_add_u32_e32 v0, s5, v12
	v_readlane_b32 s64, v253, 25
	v_ashrrev_i32_e32 v1, 31, v0
	v_readlane_b32 s74, v253, 35
	v_readlane_b32 s75, v253, 36
	v_readlane_b32 s65, v253, 26
	v_readlane_b32 s66, v253, 27
	v_lshl_add_u64 v[0:1], v[0:1], 2, s[74:75]
	global_load_dword v0, v[0:1], off
	v_lshl_add_u32 v1, v12, 2, 0
	v_add_u32_e32 v1, 0x20800, v1
	v_readlane_b32 s67, v253, 28
	v_readlane_b32 s68, v253, 29
	v_readlane_b32 s69, v253, 30
	v_readlane_b32 s70, v253, 31
	v_readlane_b32 s71, v253, 32
	v_readlane_b32 s72, v253, 33
	v_readlane_b32 s73, v253, 34
	v_readlane_b32 s76, v253, 37
	v_readlane_b32 s77, v253, 38
	v_readlane_b32 s78, v253, 39
	v_readlane_b32 s79, v253, 40
	s_waitcnt vmcnt(0)
	ds_write_b32 v1, v0

; __device__ __forceinline__ unsigned pk2(float lo, float hi) { f32x2 v = {lo, hi}; bf2_t b = __builtin_convertvector(v, bf2_t); return __builtin_bit_cast(unsigned, b); }
; __device__ __forceinline__ void attn_unit(LAS unsigned char* lds, const Args& a, int layer, int b, int nb, int kh, float shift2) {
;     ...
;     la += __shfl_xor(la, 32); lb += __shfl_xor(lb, 32);
;     const float inva = 1.0f / (la + sinkterm), invb = 1.0f / (lb + sinkterm);
;     bf16_t* opa = MIX + tok0 * 1024 + hq * 64 + 4 * hi; bf16_t* opb = opa + 32 * 1024;
; #pragma unroll
;     for (int j = 0; j < 4; ++j) {
;         u32x2 w0, w1, w2, w3;
;         w0.x = pk2(oa0[4 * j] * inva, oa0[4 * j + 1] * inva); w0.y = pk2(oa0[4 * j + 2] * inva, oa0[4 * j + 3] * inva);
;         w1.x = pk2(oa1[4 * j] * inva, oa1[4 * j + 1] * inva); w1.y = pk2(oa1[4 * j + 2] * inva, oa1[4 * j + 3] * inva);
;         w2.x = pk2(ob0[4 * j] * invb, ob0[4 * j + 1] * invb); w2.y = pk2(ob0[4 * j + 2] * invb, ob0[4 * j + 3] * invb);
;         w3.x = pk2(ob1[4 * j] * invb, ob1[4 * j + 1] * invb); w3.y = pk2(ob1[4 * j + 2] * invb, ob1[4 * j + 3] * invb);
;         *(u32x2*)(opa + 8 * j) = w0; *(u32x2*)(opa + 32 + 8 * j) = w1; *(u32x2*)(opb + 8 * j) = w2; *(u32x2*)(opb + 32 + 8 * j) = w3;
;     }
.LBB0_491:
	ds_bpermute_b32 v64, v145, v149
	s_mov_b32 s1, 0x3fb8aa3b
	v_fma_f32 v65, v186, s1, -v185
	v_exp_f32_e32 v65, v65
	ds_bpermute_b32 v66, v145, v148
	s_waitcnt lgkmcnt(1)
	v_add_f32_e32 v64, v149, v64
	v_lshlrev_b32_e32 v200, 11, v144
	v_add_f32_e32 v64, v65, v64
	v_div_scale_f32 v67, s[8:9], v64, v64, 1.0
	v_rcp_f32_e32 v68, v67
	v_div_scale_f32 v69, vcc, 1.0, v64, 1.0
	s_waitcnt lgkmcnt(0)
	v_add_f32_e32 v66, v148, v66
	v_fma_f32 v70, -v67, v68, 1.0
	v_fmac_f32_e32 v68, v70, v68
	v_mul_f32_e32 v70, v69, v68
	v_fma_f32 v71, -v67, v70, v69
	v_add_f32_e32 v65, v65, v66
	v_fmac_f32_e32 v70, v71, v68
	v_div_scale_f32 v66, s[8:9], v65, v65, 1.0
	v_fma_f32 v67, -v67, v70, v69
	v_rcp_f32_e32 v69, v66
	v_div_fmas_f32 v67, v67, v68, v70
	v_div_fixup_f32 v64, v67, v64, 1.0
	v_readlane_b32 s8, v254, 45
	v_fma_f32 v67, -v66, v69, 1.0
	v_fmac_f32_e32 v69, v67, v69
	v_div_scale_f32 v67, vcc, 1.0, v65, 1.0
	v_mul_f32_e32 v68, v67, v69
	v_fma_f32 v70, -v66, v68, v67
	v_fmac_f32_e32 v68, v70, v69
	v_fma_f32 v66, -v66, v68, v67
	v_readlane_b32 s9, v254, 46
	v_div_fmas_f32 v66, v66, v69, v68
	v_div_fixup_f32 v66, v66, v65, 1.0
	v_lshl_add_u64 v[68:69], s[8:9], 0, v[200:201]
	v_lshl_add_u64 v[68:69], v[146:147], 1, v[68:69]
	v_lshlrev_b32_e32 v200, 1, v187
	v_lshl_add_u64 v[68:69], v[68:69], 0, v[200:201]
	v_and_b32_e32 v72, 32, v243
	v_mov_b32_e32 v73, 0
	v_lshrrev_b32_e32 v72, 2, v72
	s_mov_b32 s1, 0x10000
	v_lshl_add_u64 v[68:69], v[68:69], 0, v[72:73]
	v_pk_mul_f32 v[16:17], v[16:17], v[64:65] op_sel_hi:[1,0]
	v_pk_mul_f32 v[18:19], v[18:19], v[64:65] op_sel_hi:[1,0]
	v_pk_mul_f32 v[20:21], v[20:21], v[64:65] op_sel_hi:[1,0]
	v_pk_mul_f32 v[22:23], v[22:23], v[64:65] op_sel_hi:[1,0]
	v_pk_mul_f32 v[24:25], v[24:25], v[64:65] op_sel_hi:[1,0]
	v_pk_mul_f32 v[26:27], v[26:27], v[64:65] op_sel_hi:[1,0]
	v_pk_mul_f32 v[28:29], v[28:29], v[64:65] op_sel_hi:[1,0]
	v_pk_mul_f32 v[30:31], v[30:31], v[64:65] op_sel_hi:[1,0]
	v_pk_mul_f32 v[48:49], v[48:49], v[64:65] op_sel_hi:[1,0]
	v_pk_mul_f32 v[50:51], v[50:51], v[64:65] op_sel_hi:[1,0]
	v_pk_mul_f32 v[52:53], v[52:53], v[64:65] op_sel_hi:[1,0]
	v_pk_mul_f32 v[54:55], v[54:55], v[64:65] op_sel_hi:[1,0]
	v_pk_mul_f32 v[56:57], v[56:57], v[64:65] op_sel_hi:[1,0]
	v_pk_mul_f32 v[58:59], v[58:59], v[64:65] op_sel_hi:[1,0]
	v_pk_mul_f32 v[60:61], v[60:61], v[64:65] op_sel_hi:[1,0]
	v_pk_mul_f32 v[62:63], v[62:63], v[64:65] op_sel_hi:[1,0]
	v_pk_mul_f32 v[32:33], v[32:33], v[66:67] op_sel_hi:[1,0]
	v_pk_mul_f32 v[34:35], v[34:35], v[66:67] op_sel_hi:[1,0]
	v_pk_mul_f32 v[36:37], v[36:37], v[66:67] op_sel_hi:[1,0]
	v_pk_mul_f32 v[38:39], v[38:39], v[66:67] op_sel_hi:[1,0]
	v_pk_mul_f32 v[40:41], v[40:41], v[66:67] op_sel_hi:[1,0]
	v_pk_mul_f32 v[42:43], v[42:43], v[66:67] op_sel_hi:[1,0]
	v_pk_mul_f32 v[44:45], v[44:45], v[66:67] op_sel_hi:[1,0]
	v_pk_mul_f32 v[46:47], v[46:47], v[66:67] op_sel_hi:[1,0]
	v_pk_mul_f32 v[0:1], v[0:1], v[66:67] op_sel_hi:[1,0]
	v_pk_mul_f32 v[2:3], v[2:3], v[66:67] op_sel_hi:[1,0]
	v_pk_mul_f32 v[4:5], v[4:5], v[66:67] op_sel_hi:[1,0]
	v_pk_mul_f32 v[6:7], v[6:7], v[66:67] op_sel_hi:[1,0]
	v_pk_mul_f32 v[8:9], v[8:9], v[66:67] op_sel_hi:[1,0]
	v_pk_mul_f32 v[10:11], v[10:11], v[66:67] op_sel_hi:[1,0]
	v_pk_mul_f32 v[12:13], v[12:13], v[66:67] op_sel_hi:[1,0]
	v_pk_mul_f32 v[14:15], v[14:15], v[66:67] op_sel_hi:[1,0]
	v_add_co_u32_e32 v70, vcc, s1, v68
	s_nop 1
	v_addc_co_u32_e32 v71, vcc, 0, v69, vcc
	v_cvt_pk_bf16_f32 v16, v16, v17
	v_cvt_pk_bf16_f32 v17, v18, v19
	v_cvt_pk_bf16_f32 v18, v20, v21
	v_cvt_pk_bf16_f32 v19, v22, v23
	v_cvt_pk_bf16_f32 v24, v24, v25
	v_cvt_pk_bf16_f32 v25, v26, v27
	v_cvt_pk_bf16_f32 v26, v28, v29
	v_cvt_pk_bf16_f32 v27, v30, v31
	v_cvt_pk_bf16_f32 v48, v48, v49
	v_cvt_pk_bf16_f32 v49, v50, v51
	v_cvt_pk_bf16_f32 v50, v52, v53
	v_cvt_pk_bf16_f32 v51, v54, v55
	v_cvt_pk_bf16_f32 v56, v56, v57
	v_cvt_pk_bf16_f32 v57, v58, v59
	v_cvt_pk_bf16_f32 v58, v60, v61
	v_cvt_pk_bf16_f32 v59, v62, v63
	v_cvt_pk_bf16_f32 v32, v32, v33
	v_cvt_pk_bf16_f32 v33, v34, v35
	v_cvt_pk_bf16_f32 v34, v36, v37
	v_cvt_pk_bf16_f32 v35, v38, v39
	v_cvt_pk_bf16_f32 v40, v40, v41
	v_cvt_pk_bf16_f32 v41, v42, v43
	v_cvt_pk_bf16_f32 v42, v44, v45
	v_cvt_pk_bf16_f32 v43, v46, v47
	v_cvt_pk_bf16_f32 v0, v0, v1
	v_cvt_pk_bf16_f32 v1, v2, v3
	v_cvt_pk_bf16_f32 v2, v4, v5
	v_cvt_pk_bf16_f32 v3, v6, v7
	v_cvt_pk_bf16_f32 v8, v8, v9
	v_cvt_pk_bf16_f32 v9, v10, v11
	v_cvt_pk_bf16_f32 v10, v12, v13
	v_cvt_pk_bf16_f32 v11, v14, v15
	s_nop 1
	v_permlane32_swap_b32_e32 v16, v18
	v_permlane32_swap_b32_e32 v17, v19
	v_permlane32_swap_b32_e32 v24, v26
	v_permlane32_swap_b32_e32 v25, v27
	v_permlane32_swap_b32_e32 v48, v50
	v_permlane32_swap_b32_e32 v49, v51
	v_permlane32_swap_b32_e32 v56, v58
	v_permlane32_swap_b32_e32 v57, v59
	v_permlane32_swap_b32_e32 v32, v34
	v_permlane32_swap_b32_e32 v33, v35
	v_permlane32_swap_b32_e32 v40, v42
	v_permlane32_swap_b32_e32 v41, v43
	v_permlane32_swap_b32_e32 v0, v2
	v_permlane32_swap_b32_e32 v1, v3
	v_permlane32_swap_b32_e32 v8, v10
	v_permlane32_swap_b32_e32 v9, v11
	global_store_dwordx4 v[68:69], v[16:19], off
	global_store_dwordx4 v[68:69], v[24:27], off offset:32
	global_store_dwordx4 v[68:69], v[48:51], off offset:64
	global_store_dwordx4 v[68:69], v[56:59], off offset:96
	global_store_dwordx4 v[70:71], v[32:35], off
	global_store_dwordx4 v[70:71], v[40:43], off offset:32
	global_store_dwordx4 v[70:71], v[0:3], off offset:64
	global_store_dwordx4 v[70:71], v[8:11], off offset:96
	s_nop 1
	v_mov_b32_e32 v8, v236
	s_barrier
; #define PG8_STAGE(bufoff, gbase, voff) do { _Pragma("unroll") for (int _i = 0; _i < 2; ++_i) \
;         __builtin_amdgcn_global_load_lds((const unsigned*)((const char*)(gbase) + (voff)[_i]), (LAS unsigned*)(lds + (bufoff) + ldsw + _i * 8192), 16, 0, 0); } while (0)
; template <class Epi, class Sched, bool ALIGN_EPI = true, bool SP2 = true, class Pre = NoPre>
; __device__ __forceinline__ void gemm_phase(LAS unsigned char* lds, const Gemm g, const Sched& S, const Epi& E, const Pre& pre = Pre()) {
;     ...
;     for (int i = 0; i < 2; ++i) { int R, C; stage_rc(tid * 16 + i * 8192, R, C); const int Rb = Epi::PERM ? ((R & ~31) + perm32(R & 31)) : R;
;         voffA[i] = (unsigned)(R * g.lda + C) * 2u; voffB[i] = (unsigned)(Rb * g.ldb + C) * 2u; }
;     const size_t kstep = (size_t)(BK * 2);
;     const size_t hsA = (size_t)HALF * g.lda * 2, hsB = (size_t)HALF * g.ldb * 2;
;     const unsigned ldsw = (unsigned)wid * 1024u;
;     const int aoff = lds_byte(wr * 64 + fr, fq * 8), boff = lds_byte(wc * 32 + fr, fq * 8);
;     ...
;         PG8_STAGE(PG8_SB(0, 0), cB, voffB); PG8_STAGE(PG8_SB(0, 1), cB + hsB, voffB); PG8_STAGE(PG8_SA(0, 0), cA, voffA); PG8_STAGE(PG8_SA(0, 1), cA + hsA, voffA);
	s_cmpk_gt_u32 s20, 0x7f
	v_readfirstlane_b32 s7, v8
	s_mov_b32 s42, s82
	s_cbranch_scc1 .LBB0_511
	v_lshlrev_b32_e32 v0, 4, v8
	v_add_u32_e32 v1, 0x2000, v0
	v_ashrrev_i32_e32 v2, 31, v1
	v_lshrrev_b32_e32 v2, 22, v2
	v_add_u32_e32 v2, v1, v2
	v_ashrrev_i32_e32 v2, 10, v2
	v_mul_i32_i24_e32 v3, 0x400, v2
	v_sub_u32_e32 v1, v1, v3
	v_lshrrev_b32_e32 v3, 4, v1
	v_bitop3_b32 v1, v3, v1, 32 bitop3:0x6c
	v_ashrrev_i32_e32 v3, 31, v1
	v_lshrrev_b32_e32 v3, 26, v3
	v_add_u32_e32 v3, v1, v3
	v_lshlrev_b32_e32 v5, 3, v2
	v_ashrrev_i32_e32 v4, 6, v3
	v_and_b32_e32 v5, -16, v5
	v_add_u32_e32 v5, v4, v5
	s_mov_b32 s12, s3
	v_and_b32_e32 v4, 3, v4
	s_mov_b32 s3, 0xffffe0
	v_lshrrev_b32_e32 v6, 2, v5
	v_lshlrev_b32_e32 v7, 1, v5
	v_and_b32_e32 v3, 0xc0, v3
	v_and_or_b32 v4, v5, s3, v4
	v_and_b32_e32 v6, 4, v6
	v_and_b32_e32 v7, 24, v7
	v_lshlrev_b32_e32 v2, 5, v2
	v_sub_u32_e32 v1, v1, v3
	v_or3_b32 v4, v4, v6, v7
	v_and_b32_e32 v2, 32, v2
	v_ashrrev_i16_sdwa v1, v252, sext(v1) dst_sel:DWORD dst_unused:UNUSED_PAD src0_sel:DWORD src1_sel:BYTE_0
	s_movk_i32 s1, 0x300
	v_mul_u32_u24_e32 v4, 0x300, v4
	v_add_u32_sdwa v1, v2, sext(v1) dst_sel:DWORD dst_unused:UNUSED_PAD src0_sel:DWORD src1_sel:WORD_0
	v_mul_lo_u32 v2, v5, s1
	v_add_lshl_u32 v128, v4, v1, 1
	v_add_lshl_u32 v130, v1, v2, 1
	v_bfe_i32 v1, v8, 27, 1
	v_lshrrev_b32_e32 v1, 22, v1
	v_add_u32_e32 v1, v0, v1
	v_and_b32_e32 v1, 0xfffffc00, v1
	v_sub_u32_e32 v0, v0, v1
	s_ashr_i32 s22, s7, 6
	v_lshrrev_b32_e32 v1, 4, v0
	v_ashrrev_i32_e32 v3, 31, v8
	s_ashr_i32 s23, s7, 8
	s_lshl_b32 s27, s22, 10
	v_bitop3_b32 v0, v1, v0, 32 bitop3:0x6c
	v_lshrrev_b32_e32 v3, 26, v3
	s_add_u32 s5, s92, s97
	v_ashrrev_i32_e32 v1, 31, v0
	v_add_u32_e32 v3, v8, v3
	s_addc_u32 s11, s93, 0
	v_lshrrev_b32_e32 v1, 26, v1
	v_ashrrev_i32_e32 v3, 6, v3
	s_lshr_b32 s8, s20, 2
	s_bfe_u32 s9, s49, 0x10004
	v_add_u32_e32 v1, v0, v1
	v_lshlrev_b32_e32 v4, 3, v3
	s_mul_i32 s10, s8, 0x60000
	s_mul_i32 s16, s9, 0x30000
	v_ashrrev_i32_e32 v2, 6, v1
	v_and_b32_e32 v4, -16, v4
	s_add_i32 s16, s10, s16
	v_add_u32_e32 v4, v2, v4
	s_lshl_b32 s20, s16, 1
	s_mul_i32 s16, s13, 0x30000
	v_and_b32_e32 v2, 3, v2
	v_lshrrev_b32_e32 v5, 2, v4
	v_lshlrev_b32_e32 v6, 1, v4
	v_and_b32_e32 v1, 0xc0, v1
	s_add_i32 s10, s10, s16
	v_and_or_b32 v2, v4, s3, v2
	v_and_b32_e32 v5, 4, v5
	v_and_b32_e32 v6, 24, v6
	v_lshlrev_b32_e32 v3, 5, v3
	v_sub_u32_e32 v0, v0, v1
	s_lshl_b32 s10, s10, 1
	v_or3_b32 v2, v2, v5, v6
	v_and_b32_e32 v3, 32, v3
	v_ashrrev_i16_sdwa v0, v252, sext(v0) dst_sel:DWORD dst_unused:UNUSED_PAD src0_sel:DWORD src1_sel:BYTE_0
	s_add_u32 s10, s5, s10
	v_mul_u32_u24_e32 v2, 0x300, v2
	v_add_u32_sdwa v0, v3, sext(v0) dst_sel:DWORD dst_unused:UNUSED_PAD src0_sel:DWORD src1_sel:WORD_0
	s_addc_u32 s11, s11, 0
	s_add_i32 s30, s27, 0
	v_add_lshl_u32 v200, v2, v0, 1
	s_add_i32 m0, s30, 0x10000
	v_mul_lo_u32 v1, v4, s1
	global_load_lds_dwordx4 v200, s[10:11]
	s_add_i32 m0, s30, 0x12000
	s_add_u32 s16, s10, 0x30000
	global_load_lds_dwordx4 v128, s[10:11]
	s_addc_u32 s17, s11, 0
	s_add_i32 m0, s30, 0x14000
	v_add_lshl_u32 v132, v0, v1, 1
	global_load_lds_dwordx4 v200, s[16:17]
	s_add_i32 m0, s30, 0x16000
	v_mov_b32_e32 v129, v201
	global_load_lds_dwordx4 v128, s[16:17]
	s_add_u32 s16, s44, s20
	s_addc_u32 s17, s45, 0
	s_add_i32 s5, s30, 0x2000
	s_mov_b32 m0, s30
	s_add_u32 s20, s16, 0x30000
	global_load_lds_dwordx4 v132, s[16:17]
	s_mov_b32 m0, s5
	s_addc_u32 s21, s17, 0
	s_add_i32 s31, s30, 0x4000
	global_load_lds_dwordx4 v130, s[16:17]
	s_mov_b32 m0, s31
	s_add_i32 s38, s30, 0x6000
	global_load_lds_dwordx4 v132, s[20:21]
	s_mov_b32 m0, s38
	v_mov_b32_e32 v133, v201
	global_load_lds_dwordx4 v130, s[20:21]
	v_mov_b32_e32 v131, v201
	v_lshl_add_u64 v[6:7], s[10:11], 0, v[200:201]
	v_lshl_add_u64 v[4:5], s[10:11], 0, v[128:129]
	v_lshl_add_u64 v[2:3], s[16:17], 0, v[132:133]
	s_cmp_lg_u32 s23, 1
	v_lshl_add_u64 v[0:1], s[16:17], 0, v[130:131]
	s_cbranch_scc1 .LBB0_494
	s_barrier

; __device__ __forceinline__ unsigned pk2(float lo, float hi) { f32x2 v = {lo, hi}; bf2_t b = __builtin_convertvector(v, bf2_t); return __builtin_bit_cast(unsigned, b); }
; __device__ __forceinline__ void attn_unit(LAS unsigned char* lds, const Args& a, int layer, int b, int nb, int kh, float shift2) {
;     ...
;     la += __shfl_xor(la, 32); lb += __shfl_xor(lb, 32);
;     const float inva = 1.0f / (la + sinkterm), invb = 1.0f / (lb + sinkterm);
;     bf16_t* opa = MIX + tok0 * 1024 + hq * 64 + 4 * hi; bf16_t* opb = opa + 32 * 1024;
; #pragma unroll
;     for (int j = 0; j < 4; ++j) {
;         u32x2 w0, w1, w2, w3;
;         w0.x = pk2(oa0[4 * j] * inva, oa0[4 * j + 1] * inva); w0.y = pk2(oa0[4 * j + 2] * inva, oa0[4 * j + 3] * inva);
;         w1.x = pk2(oa1[4 * j] * inva, oa1[4 * j + 1] * inva); w1.y = pk2(oa1[4 * j + 2] * inva, oa1[4 * j + 3] * inva);
;         w2.x = pk2(ob0[4 * j] * invb, ob0[4 * j + 1] * invb); w2.y = pk2(ob0[4 * j + 2] * invb, ob0[4 * j + 3] * invb);
;         w3.x = pk2(ob1[4 * j] * invb, ob1[4 * j + 1] * invb); w3.y = pk2(ob1[4 * j + 2] * invb, ob1[4 * j + 3] * invb);
;         *(u32x2*)(opa + 8 * j) = w0; *(u32x2*)(opa + 32 + 8 * j) = w1; *(u32x2*)(opb + 8 * j) = w2; *(u32x2*)(opb + 32 + 8 * j) = w3;
;     }
.LBB0_553:
	ds_bpermute_b32 v64, v184, v149
	s_mov_b32 s1, 0x3fb8aa3b
	v_fma_f32 v65, v186, s1, -v185
	v_exp_f32_e32 v65, v65
	ds_bpermute_b32 v66, v184, v148
	s_waitcnt lgkmcnt(1)
	v_add_f32_e32 v64, v149, v64
	v_lshlrev_b32_e32 v200, 1, v187
	v_add_f32_e32 v64, v65, v64
	v_div_scale_f32 v67, s[8:9], v64, v64, 1.0
	v_rcp_f32_e32 v68, v67
	v_div_scale_f32 v69, vcc, 1.0, v64, 1.0
	s_waitcnt lgkmcnt(0)
	v_add_f32_e32 v66, v148, v66
	v_fma_f32 v70, -v67, v68, 1.0
	v_fmac_f32_e32 v68, v70, v68
	v_mul_f32_e32 v70, v69, v68
	v_fma_f32 v71, -v67, v70, v69
	v_add_f32_e32 v65, v65, v66
	v_fmac_f32_e32 v70, v71, v68
	v_div_scale_f32 v66, s[8:9], v65, v65, 1.0
	v_fma_f32 v67, -v67, v70, v69
	v_rcp_f32_e32 v69, v66
	v_div_fmas_f32 v67, v67, v68, v70
	v_div_fixup_f32 v64, v67, v64, 1.0
	v_readlane_b32 s8, v254, 45
	v_fma_f32 v67, -v66, v69, 1.0
	v_fmac_f32_e32 v69, v67, v69
	v_div_scale_f32 v67, vcc, 1.0, v65, 1.0
	v_mul_f32_e32 v68, v67, v69
	v_fma_f32 v70, -v66, v68, v67
	v_fmac_f32_e32 v68, v70, v69
	v_fma_f32 v66, -v66, v68, v67
	v_div_fmas_f32 v66, v66, v69, v68
	v_lshlrev_b64 v[68:69], 11, v[146:147]
	v_readlane_b32 s9, v254, 46
	v_div_fixup_f32 v66, v66, v65, 1.0
	v_lshl_add_u64 v[68:69], s[8:9], 0, v[68:69]
	v_lshl_add_u64 v[68:69], v[144:145], 1, v[68:69]
	v_lshl_add_u64 v[68:69], v[68:69], 0, v[200:201]
	v_and_b32_e32 v72, 32, v243
	v_mov_b32_e32 v73, 0
	v_lshrrev_b32_e32 v72, 2, v72
	s_mov_b32 s1, 0x10000
	v_lshl_add_u64 v[68:69], v[68:69], 0, v[72:73]
	v_pk_mul_f32 v[16:17], v[16:17], v[64:65] op_sel_hi:[1,0]
	v_pk_mul_f32 v[18:19], v[18:19], v[64:65] op_sel_hi:[1,0]
	v_pk_mul_f32 v[20:21], v[20:21], v[64:65] op_sel_hi:[1,0]
	v_pk_mul_f32 v[22:23], v[22:23], v[64:65] op_sel_hi:[1,0]
	v_pk_mul_f32 v[24:25], v[24:25], v[64:65] op_sel_hi:[1,0]
	v_pk_mul_f32 v[26:27], v[26:27], v[64:65] op_sel_hi:[1,0]
	v_pk_mul_f32 v[28:29], v[28:29], v[64:65] op_sel_hi:[1,0]
	v_pk_mul_f32 v[30:31], v[30:31], v[64:65] op_sel_hi:[1,0]
	v_pk_mul_f32 v[48:49], v[48:49], v[64:65] op_sel_hi:[1,0]
	v_pk_mul_f32 v[50:51], v[50:51], v[64:65] op_sel_hi:[1,0]
	v_pk_mul_f32 v[52:53], v[52:53], v[64:65] op_sel_hi:[1,0]
	v_pk_mul_f32 v[54:55], v[54:55], v[64:65] op_sel_hi:[1,0]
	v_pk_mul_f32 v[56:57], v[56:57], v[64:65] op_sel_hi:[1,0]
	v_pk_mul_f32 v[58:59], v[58:59], v[64:65] op_sel_hi:[1,0]
	v_pk_mul_f32 v[60:61], v[60:61], v[64:65] op_sel_hi:[1,0]
	v_pk_mul_f32 v[62:63], v[62:63], v[64:65] op_sel_hi:[1,0]
	v_pk_mul_f32 v[32:33], v[32:33], v[66:67] op_sel_hi:[1,0]
	v_pk_mul_f32 v[34:35], v[34:35], v[66:67] op_sel_hi:[1,0]
	v_pk_mul_f32 v[36:37], v[36:37], v[66:67] op_sel_hi:[1,0]
	v_pk_mul_f32 v[38:39], v[38:39], v[66:67] op_sel_hi:[1,0]
	v_pk_mul_f32 v[40:41], v[40:41], v[66:67] op_sel_hi:[1,0]
	v_pk_mul_f32 v[42:43], v[42:43], v[66:67] op_sel_hi:[1,0]
	v_pk_mul_f32 v[44:45], v[44:45], v[66:67] op_sel_hi:[1,0]
	v_pk_mul_f32 v[46:47], v[46:47], v[66:67] op_sel_hi:[1,0]
	v_pk_mul_f32 v[0:1], v[0:1], v[66:67] op_sel_hi:[1,0]
	v_pk_mul_f32 v[2:3], v[2:3], v[66:67] op_sel_hi:[1,0]
	v_pk_mul_f32 v[4:5], v[4:5], v[66:67] op_sel_hi:[1,0]
	v_pk_mul_f32 v[6:7], v[6:7], v[66:67] op_sel_hi:[1,0]
	v_pk_mul_f32 v[8:9], v[8:9], v[66:67] op_sel_hi:[1,0]
	v_pk_mul_f32 v[10:11], v[10:11], v[66:67] op_sel_hi:[1,0]
	v_pk_mul_f32 v[12:13], v[12:13], v[66:67] op_sel_hi:[1,0]
	v_pk_mul_f32 v[14:15], v[14:15], v[66:67] op_sel_hi:[1,0]
	v_add_co_u32_e32 v70, vcc, s1, v68
	s_nop 1
	v_addc_co_u32_e32 v71, vcc, 0, v69, vcc
	v_cvt_pk_bf16_f32 v16, v16, v17
	v_cvt_pk_bf16_f32 v17, v18, v19
	v_cvt_pk_bf16_f32 v18, v20, v21
	v_cvt_pk_bf16_f32 v19, v22, v23
	v_cvt_pk_bf16_f32 v24, v24, v25
	v_cvt_pk_bf16_f32 v25, v26, v27
	v_cvt_pk_bf16_f32 v26, v28, v29
	v_cvt_pk_bf16_f32 v27, v30, v31
	v_cvt_pk_bf16_f32 v48, v48, v49
	v_cvt_pk_bf16_f32 v49, v50, v51
	v_cvt_pk_bf16_f32 v50, v52, v53
	v_cvt_pk_bf16_f32 v51, v54, v55
	v_cvt_pk_bf16_f32 v56, v56, v57
	v_cvt_pk_bf16_f32 v57, v58, v59
	v_cvt_pk_bf16_f32 v58, v60, v61
	v_cvt_pk_bf16_f32 v59, v62, v63
	v_cvt_pk_bf16_f32 v32, v32, v33
	v_cvt_pk_bf16_f32 v33, v34, v35
	v_cvt_pk_bf16_f32 v34, v36, v37
	v_cvt_pk_bf16_f32 v35, v38, v39
	v_cvt_pk_bf16_f32 v40, v40, v41
	v_cvt_pk_bf16_f32 v41, v42, v43
	v_cvt_pk_bf16_f32 v42, v44, v45
	v_cvt_pk_bf16_f32 v43, v46, v47
	v_cvt_pk_bf16_f32 v0, v0, v1
	v_cvt_pk_bf16_f32 v1, v2, v3
	v_cvt_pk_bf16_f32 v2, v4, v5
	v_cvt_pk_bf16_f32 v3, v6, v7
	v_cvt_pk_bf16_f32 v8, v8, v9
	v_cvt_pk_bf16_f32 v9, v10, v11
	v_cvt_pk_bf16_f32 v10, v12, v13
	v_cvt_pk_bf16_f32 v11, v14, v15
	s_nop 1
	v_permlane32_swap_b32_e32 v16, v18
	v_permlane32_swap_b32_e32 v17, v19
	v_permlane32_swap_b32_e32 v24, v26
	v_permlane32_swap_b32_e32 v25, v27
	v_permlane32_swap_b32_e32 v48, v50
	v_permlane32_swap_b32_e32 v49, v51
	v_permlane32_swap_b32_e32 v56, v58
	v_permlane32_swap_b32_e32 v57, v59
	v_permlane32_swap_b32_e32 v32, v34
	v_permlane32_swap_b32_e32 v33, v35
	v_permlane32_swap_b32_e32 v40, v42
	v_permlane32_swap_b32_e32 v41, v43
	v_permlane32_swap_b32_e32 v0, v2
	v_permlane32_swap_b32_e32 v1, v3
	v_permlane32_swap_b32_e32 v8, v10
	v_permlane32_swap_b32_e32 v9, v11
	global_store_dwordx4 v[68:69], v[16:19], off
	global_store_dwordx4 v[68:69], v[24:27], off offset:32
	global_store_dwordx4 v[68:69], v[48:51], off offset:64
	global_store_dwordx4 v[68:69], v[56:59], off offset:96
	global_store_dwordx4 v[70:71], v[32:35], off
	global_store_dwordx4 v[70:71], v[40:43], off offset:32
	global_store_dwordx4 v[70:71], v[0:3], off offset:64
	global_store_dwordx4 v[70:71], v[8:11], off offset:96
	s_nop 1
	s_barrier
